# P3: R and GS tiles of the unit touched toward L2 by one load per wave and K iteration (waits 9,8,9,9)
# speedup vs baseline: 1.0011x; 1.0011x over previous
.LBB0_584:
	s_waitcnt lgkmcnt(0)
	v_and_b32_e32 v1, 15, v0
	s_and_b32 s4, s1, 3
	v_and_b32_e32 v2, 48, v0
	s_waitcnt lgkmcnt(0)
	v_lshlrev_b32_e32 v3, 6, v1
	v_lshlrev_b32_e32 v0, 2, v0
	s_lshl_b32 s3, s3, 13
	v_or_b32_e32 v4, v3, v2
	v_and_b32_e32 v0, 32, v0
	s_lshl_b32 s5, s4, 12
	v_bitop3_b32 v3, v3, v0, v2 bitop3:0x36
	v_bitop3_b32 v5, v4, s3, v0 bitop3:0xde
	v_bitop3_b32 v0, v4, s5, v0 bitop3:0xde
	s_waitcnt vmcnt(8)
	s_barrier
	s_add_i32 s77, s31, 0x18000
	v_readlane_b32 s5, v253, 8
	s_add_i32 s78, s31, 0x1a000
	v_readlane_b32 s8, v254, 6
	s_add_i32 s79, s31, 0x8000
	v_readlane_b32 s9, v254, 7
	v_readlane_b32 s10, v254, 8
	v_readlane_b32 s11, v254, 9
	v_readlane_b32 s5, v253, 10
	s_add_i32 s82, s31, 0xa000
	s_add_i32 s83, s31, 0x1c000
	v_readlane_b32 s5, v253, 12
	s_add_i32 s84, s31, 0x1e000
	s_and_b32 s5, s0, 0xfffff00
	s_lshl_b32 s4, s4, 6
	s_or_b32 s4, s4, s5
	s_add_i32 s85, s31, 0xc000
	s_cmpk_lt_u32 s0, 0x100
	v_or3_b32 v1, s4, v2, v1
	s_cselect_b64 s[4:5], -1, 0
	s_lshl_b32 s0, s1, 13
	s_and_b32 s1, s2, 0x400
	s_waitcnt vmcnt(6)
	s_or_b32 s1, s3, s1
	v_lshlrev_b32_e32 v220, 4, v1
	v_lshrrev_b32_e32 v99, 4, v220
	v_and_b32_e32 v100, 31, v99
	v_lshlrev_b32_e32 v100, 7, v100
	v_bfe_u32 v101, v99, 5, 1
	v_lshl_or_b32 v100, v101, 2, v100
	v_lshrrev_b32_e32 v99, 6, v99
	v_lshl_or_b32 v99, v99, 12, v100
	v_writelane_b32 v254, s4, 43
	s_and_b32 s0, s0, 0x4000
	v_or_b32_e32 v1, s1, v3
	v_mov_b32_e32 v221, v81
	v_writelane_b32 v254, s5, 44
	v_add_u32_e32 v222, s0, v1
	v_mov_b32_e32 v223, v81
	s_add_i32 s86, s31, 0xe000
	s_mov_b32 s87, 0
	v_add_u32_e32 v226, 0x100, v0
	v_add_u32_e32 v227, 0x100, v5
	v_readlane_b32 s92, v253, 4
	v_readlane_b32 s0, v253, 6
	v_readlane_b32 s38, v253, 11
	v_readlane_b32 s96, v253, 9
	s_barrier
	s_branch .LBB0_587

.LBB0_594:
	v_add_u32_e32 v80, 0x10000, v226
	ds_read_b128 v[152:155], v80
	ds_read_b128 v[156:159], v80 offset:1024
	ds_read_b128 v[160:163], v80 offset:2048
	ds_read_b128 v[164:167], v80 offset:3072
	v_add_u32_e32 v80, 0x14000, v226
	ds_read_b128 v[168:171], v80
	ds_read_b128 v[172:175], v80 offset:1024
	ds_read_b128 v[176:179], v80 offset:2048
	ds_read_b128 v[180:183], v80 offset:3072
	s_add_i32 s97, s96, s39
	s_add_i32 s94, s97, 0x8000
	s_add_i32 s95, s93, s39
	s_cmp_eq_u32 s39, 0x78000
	s_cselect_b32 s36, vcc_lo, s94
	s_cselect_b32 s95, vcc_hi, s95
	s_or_b32 s94, s36, 0x4000
	ds_read_b128 v[184:187], v227
	ds_read_b128 v[188:191], v227 offset:1024
	ds_read_b128 v[192:195], v227 offset:2048
	ds_read_b128 v[196:199], v227 offset:3072
	ds_read_b128 v[200:203], v227 offset:4096
	ds_read_b128 v[204:207], v227 offset:5120
	ds_read_b128 v[228:231], v227 offset:6144
	ds_read_b128 v[240:243], v227 offset:7168
	s_add_i32 s97, s97, 0x84000
	s_mov_b32 m0, s85
	s_nop 0
	buffer_load_dwordx4 v224, s[60:63], s97 offen lds
	s_nop 0
	s_mov_b32 m0, s86
	s_nop 0
	buffer_load_dwordx4 v225, s[60:63], s97 offen lds
	s_waitcnt vmcnt(9)
	s_waitcnt lgkmcnt(0)
	s_barrier
	s_setprio 1
	s_waitcnt lgkmcnt(7)
	v_mfma_f32_16x16x32_bf16 v[148:151], v[152:155], v[184:187], v[148:151]
	v_mfma_f32_16x16x32_bf16 v[144:147], v[160:163], v[184:187], v[144:147]
	s_waitcnt lgkmcnt(5)
	v_mfma_f32_16x16x32_bf16 v[132:135], v[152:155], v[192:195], v[132:135]
	v_mfma_f32_16x16x32_bf16 v[128:131], v[160:163], v[192:195], v[128:131]
	s_waitcnt lgkmcnt(3)
	v_mfma_f32_16x16x32_bf16 v[116:119], v[152:155], v[200:203], v[116:119]
	v_mfma_f32_16x16x32_bf16 v[112:115], v[160:163], v[200:203], v[112:115]
	s_waitcnt lgkmcnt(1)
	v_mfma_f32_16x16x32_bf16 v[76:79], v[152:155], v[228:231], v[76:79]
	v_mfma_f32_16x16x32_bf16 v[72:75], v[160:163], v[228:231], v[72:75]
	v_mfma_f32_16x16x32_bf16 v[148:151], v[156:159], v[188:191], v[148:151]
	v_mfma_f32_16x16x32_bf16 v[144:147], v[164:167], v[188:191], v[144:147]
	v_mfma_f32_16x16x32_bf16 v[132:135], v[156:159], v[196:199], v[132:135]
	v_mfma_f32_16x16x32_bf16 v[128:131], v[164:167], v[196:199], v[128:131]
	v_mfma_f32_16x16x32_bf16 v[116:119], v[156:159], v[204:207], v[116:119]
	v_mfma_f32_16x16x32_bf16 v[112:115], v[164:167], v[204:207], v[112:115]
	s_waitcnt lgkmcnt(0)
	v_mfma_f32_16x16x32_bf16 v[76:79], v[156:159], v[240:243], v[76:79]
	v_mfma_f32_16x16x32_bf16 v[72:75], v[164:167], v[240:243], v[72:75]
	s_setprio 0
	s_setprio 1
	v_mfma_f32_16x16x32_bf16 v[140:143], v[168:171], v[184:187], v[140:143]
	v_mfma_f32_16x16x32_bf16 v[136:139], v[176:179], v[184:187], v[136:139]
	v_mfma_f32_16x16x32_bf16 v[124:127], v[168:171], v[192:195], v[124:127]
	v_mfma_f32_16x16x32_bf16 v[120:123], v[176:179], v[192:195], v[120:123]
	v_mfma_f32_16x16x32_bf16 v[108:111], v[168:171], v[200:203], v[108:111]
	v_mfma_f32_16x16x32_bf16 v[104:107], v[176:179], v[200:203], v[104:107]
	v_mfma_f32_16x16x32_bf16 v[68:71], v[168:171], v[228:231], v[68:71]
	v_mfma_f32_16x16x32_bf16 v[64:67], v[176:179], v[228:231], v[64:67]
	v_mfma_f32_16x16x32_bf16 v[140:143], v[172:175], v[188:191], v[140:143]
	v_mfma_f32_16x16x32_bf16 v[136:139], v[180:183], v[188:191], v[136:139]
	v_mfma_f32_16x16x32_bf16 v[124:127], v[172:175], v[196:199], v[124:127]
	v_mfma_f32_16x16x32_bf16 v[120:123], v[180:183], v[196:199], v[120:123]
	v_mfma_f32_16x16x32_bf16 v[108:111], v[172:175], v[204:207], v[108:111]
	v_mfma_f32_16x16x32_bf16 v[104:107], v[180:183], v[204:207], v[104:107]
	v_mfma_f32_16x16x32_bf16 v[68:71], v[172:175], v[240:243], v[68:71]
	v_mfma_f32_16x16x32_bf16 v[64:67], v[180:183], v[240:243], v[64:67]
	s_setprio 0
	s_barrier
	ds_read_b128 v[184:187], v227 offset:16384
	ds_read_b128 v[188:191], v227 offset:17408
	ds_read_b128 v[192:195], v227 offset:18432
	ds_read_b128 v[196:199], v227 offset:19456
	ds_read_b128 v[200:203], v227 offset:20480
	ds_read_b128 v[204:207], v227 offset:21504
	ds_read_b128 v[228:231], v227 offset:22528
	ds_read_b128 v[240:243], v227 offset:23552
	s_mov_b32 m0, s34
	s_nop 0
	buffer_load_dwordx4 v224, s[48:51], s95 offen lds
	s_add_i32 s97, s95, 0x80000
	s_mov_b32 m0, s55
	s_nop 0
	buffer_load_dwordx4 v225, s[48:51], s95 offen lds
	s_nop 0
	s_mov_b32 m0, s72
	s_nop 0
	buffer_load_dwordx4 v224, s[48:51], s97 offen lds
	s_nop 0
	s_mov_b32 m0, s73
	s_nop 0
	buffer_load_dwordx4 v225, s[48:51], s97 offen lds
	s_nop 0
	s_mov_b32 m0, s31
	s_nop 0
	buffer_load_dwordx4 v224, s[60:63], s36 offen lds
	s_nop 0
	s_mov_b32 m0, s74
	s_nop 0
	buffer_load_dwordx4 v225, s[60:63], s36 offen lds
	s_waitcnt vmcnt(8)
	s_waitcnt lgkmcnt(0)
	s_barrier
	s_setprio 1
	s_waitcnt lgkmcnt(7)
	v_mfma_f32_16x16x32_bf16 v[60:63], v[152:155], v[184:187], v[60:63]
	v_mfma_f32_16x16x32_bf16 v[56:59], v[160:163], v[184:187], v[56:59]
	s_waitcnt lgkmcnt(5)
	v_mfma_f32_16x16x32_bf16 v[44:47], v[152:155], v[192:195], v[44:47]
	v_mfma_f32_16x16x32_bf16 v[40:43], v[160:163], v[192:195], v[40:43]
	s_waitcnt lgkmcnt(3)
	v_mfma_f32_16x16x32_bf16 v[28:31], v[152:155], v[200:203], v[28:31]
	v_mfma_f32_16x16x32_bf16 v[24:27], v[160:163], v[200:203], v[24:27]
	s_waitcnt lgkmcnt(1)
	v_mfma_f32_16x16x32_bf16 v[12:15], v[152:155], v[228:231], v[12:15]
	v_mfma_f32_16x16x32_bf16 v[8:11], v[160:163], v[228:231], v[8:11]
	v_mfma_f32_16x16x32_bf16 v[60:63], v[156:159], v[188:191], v[60:63]
	v_mfma_f32_16x16x32_bf16 v[56:59], v[164:167], v[188:191], v[56:59]
	v_mfma_f32_16x16x32_bf16 v[44:47], v[156:159], v[196:199], v[44:47]
	v_mfma_f32_16x16x32_bf16 v[40:43], v[164:167], v[196:199], v[40:43]
	v_mfma_f32_16x16x32_bf16 v[28:31], v[156:159], v[204:207], v[28:31]
	v_mfma_f32_16x16x32_bf16 v[24:27], v[164:167], v[204:207], v[24:27]
	s_waitcnt lgkmcnt(0)
	v_mfma_f32_16x16x32_bf16 v[12:15], v[156:159], v[240:243], v[12:15]
	v_mfma_f32_16x16x32_bf16 v[8:11], v[164:167], v[240:243], v[8:11]
	s_setprio 0
	s_setprio 1
	v_mfma_f32_16x16x32_bf16 v[52:55], v[168:171], v[184:187], v[52:55]
	v_mfma_f32_16x16x32_bf16 v[48:51], v[176:179], v[184:187], v[48:51]
	v_mfma_f32_16x16x32_bf16 v[36:39], v[168:171], v[192:195], v[36:39]
	v_mfma_f32_16x16x32_bf16 v[32:35], v[176:179], v[192:195], v[32:35]
	v_mfma_f32_16x16x32_bf16 v[20:23], v[168:171], v[200:203], v[20:23]
	v_mfma_f32_16x16x32_bf16 v[16:19], v[176:179], v[200:203], v[16:19]
	v_mfma_f32_16x16x32_bf16 v[4:7], v[168:171], v[228:231], v[4:7]
	v_mfma_f32_16x16x32_bf16 v[0:3], v[176:179], v[228:231], v[0:3]
	v_mfma_f32_16x16x32_bf16 v[52:55], v[172:175], v[188:191], v[52:55]
	v_mfma_f32_16x16x32_bf16 v[48:51], v[180:183], v[188:191], v[48:51]
	v_mfma_f32_16x16x32_bf16 v[36:39], v[172:175], v[196:199], v[36:39]
	v_mfma_f32_16x16x32_bf16 v[32:35], v[180:183], v[196:199], v[32:35]
	v_mfma_f32_16x16x32_bf16 v[20:23], v[172:175], v[204:207], v[20:23]
	v_mfma_f32_16x16x32_bf16 v[16:19], v[180:183], v[204:207], v[16:19]
	v_mfma_f32_16x16x32_bf16 v[4:7], v[172:175], v[240:243], v[4:7]
	v_mfma_f32_16x16x32_bf16 v[0:3], v[180:183], v[240:243], v[0:3]
	s_setprio 0
	s_barrier
	v_add_u32_e32 v80, 0x18000, v226
	ds_read_b128 v[152:155], v80
	ds_read_b128 v[156:159], v80 offset:1024
	ds_read_b128 v[160:163], v80 offset:2048
	ds_read_b128 v[164:167], v80 offset:3072
	v_add_u32_e32 v80, 0x1c000, v226
	ds_read_b128 v[168:171], v80
	ds_read_b128 v[172:175], v80 offset:1024
	ds_read_b128 v[176:179], v80 offset:2048
	ds_read_b128 v[180:183], v80 offset:3072
	ds_read_b128 v[184:187], v227 offset:32768
	ds_read_b128 v[188:191], v227 offset:33792
	ds_read_b128 v[192:195], v227 offset:34816
	ds_read_b128 v[196:199], v227 offset:35840
	ds_read_b128 v[200:203], v227 offset:36864
	ds_read_b128 v[204:207], v227 offset:37888
	ds_read_b128 v[228:231], v227 offset:38912
	ds_read_b128 v[240:243], v227 offset:39936
	s_add_i32 s36, s36, 0x80000
	s_mov_b32 m0, s75
	s_nop 0
	buffer_load_dwordx4 v224, s[60:63], s36 offen lds
	s_nop 0
	s_mov_b32 m0, s76
	s_nop 0
	buffer_load_dwordx4 v225, s[60:63], s36 offen lds
	s_lshr_b32 s98, s39, 15
	s_sub_i32 s98, s98, 3
	s_and_b32 s98, s98, 7
	s_cmp_lt_u32 s98, 4
	s_cselect_b32 s98, s98, 0
	s_lshl_b32 s98, s98, 15
	s_cmp_ge_u32 s39, 0x40000
	s_cselect_b32 s99, 0x4000000, 0
	s_add_i32 s98, s98, s99
	s_add_u32 s98, s4, s98
	s_addc_u32 s99, s5, 0
	global_load_dword v100, v99, s[98:99]
	s_waitcnt vmcnt(9)
	s_waitcnt lgkmcnt(0)
	s_barrier
	s_setprio 1
	s_waitcnt lgkmcnt(7)
	v_mfma_f32_16x16x32_bf16 v[148:151], v[152:155], v[184:187], v[148:151]
	v_mfma_f32_16x16x32_bf16 v[144:147], v[160:163], v[184:187], v[144:147]
	s_waitcnt lgkmcnt(5)
	v_mfma_f32_16x16x32_bf16 v[132:135], v[152:155], v[192:195], v[132:135]
	v_mfma_f32_16x16x32_bf16 v[128:131], v[160:163], v[192:195], v[128:131]
	s_waitcnt lgkmcnt(3)
	v_mfma_f32_16x16x32_bf16 v[116:119], v[152:155], v[200:203], v[116:119]
	v_mfma_f32_16x16x32_bf16 v[112:115], v[160:163], v[200:203], v[112:115]
	s_waitcnt lgkmcnt(1)
	v_mfma_f32_16x16x32_bf16 v[76:79], v[152:155], v[228:231], v[76:79]
	v_mfma_f32_16x16x32_bf16 v[72:75], v[160:163], v[228:231], v[72:75]
	v_mfma_f32_16x16x32_bf16 v[148:151], v[156:159], v[188:191], v[148:151]
	v_mfma_f32_16x16x32_bf16 v[144:147], v[164:167], v[188:191], v[144:147]
	v_mfma_f32_16x16x32_bf16 v[132:135], v[156:159], v[196:199], v[132:135]
	v_mfma_f32_16x16x32_bf16 v[128:131], v[164:167], v[196:199], v[128:131]
	v_mfma_f32_16x16x32_bf16 v[116:119], v[156:159], v[204:207], v[116:119]
	v_mfma_f32_16x16x32_bf16 v[112:115], v[164:167], v[204:207], v[112:115]
	s_waitcnt lgkmcnt(0)
	v_mfma_f32_16x16x32_bf16 v[76:79], v[156:159], v[240:243], v[76:79]
	v_mfma_f32_16x16x32_bf16 v[72:75], v[164:167], v[240:243], v[72:75]
	s_setprio 0
	s_setprio 1
	v_mfma_f32_16x16x32_bf16 v[140:143], v[168:171], v[184:187], v[140:143]
	v_mfma_f32_16x16x32_bf16 v[136:139], v[176:179], v[184:187], v[136:139]
	v_mfma_f32_16x16x32_bf16 v[124:127], v[168:171], v[192:195], v[124:127]
	v_mfma_f32_16x16x32_bf16 v[120:123], v[176:179], v[192:195], v[120:123]
	v_mfma_f32_16x16x32_bf16 v[108:111], v[168:171], v[200:203], v[108:111]
	v_mfma_f32_16x16x32_bf16 v[104:107], v[176:179], v[200:203], v[104:107]
	v_mfma_f32_16x16x32_bf16 v[68:71], v[168:171], v[228:231], v[68:71]
	v_mfma_f32_16x16x32_bf16 v[64:67], v[176:179], v[228:231], v[64:67]
	v_mfma_f32_16x16x32_bf16 v[140:143], v[172:175], v[188:191], v[140:143]
	v_mfma_f32_16x16x32_bf16 v[136:139], v[180:183], v[188:191], v[136:139]
	v_mfma_f32_16x16x32_bf16 v[124:127], v[172:175], v[196:199], v[124:127]
	v_mfma_f32_16x16x32_bf16 v[120:123], v[180:183], v[196:199], v[120:123]
	v_mfma_f32_16x16x32_bf16 v[108:111], v[172:175], v[204:207], v[108:111]
	v_mfma_f32_16x16x32_bf16 v[104:107], v[180:183], v[204:207], v[104:107]
	v_mfma_f32_16x16x32_bf16 v[68:71], v[172:175], v[240:243], v[68:71]
	v_mfma_f32_16x16x32_bf16 v[64:67], v[180:183], v[240:243], v[64:67]
	s_setprio 0
	s_barrier
	ds_read_b128 v[184:187], v227 offset:49152
	ds_read_b128 v[188:191], v227 offset:50176
	ds_read_b128 v[192:195], v227 offset:51200
	ds_read_b128 v[196:199], v227 offset:52224
	ds_read_b128 v[200:203], v227 offset:53248
	ds_read_b128 v[204:207], v227 offset:54272
	ds_read_b128 v[228:231], v227 offset:55296
	ds_read_b128 v[240:243], v227 offset:56320
	s_or_b32 s36, s95, 0x4000
	s_mov_b32 m0, s77
	s_nop 0
	buffer_load_dwordx4 v224, s[48:51], s36 offen lds
	s_nop 0
	s_mov_b32 m0, s78
	s_nop 0
	buffer_load_dwordx4 v225, s[48:51], s36 offen lds
	s_add_i32 s36, s95, 0x84000
	s_mov_b32 m0, s83
	s_nop 0
	buffer_load_dwordx4 v224, s[48:51], s36 offen lds
	s_nop 0
	s_mov_b32 m0, s84
	s_nop 0
	buffer_load_dwordx4 v225, s[48:51], s36 offen lds
	s_nop 0
	s_mov_b32 m0, s79
	s_nop 0
	buffer_load_dwordx4 v224, s[60:63], s94 offen lds
	s_nop 0
	s_mov_b32 m0, s82
	s_nop 0
	buffer_load_dwordx4 v225, s[60:63], s94 offen lds
	s_waitcnt vmcnt(9)
	s_waitcnt lgkmcnt(0)
	s_barrier
	s_setprio 1
	s_waitcnt lgkmcnt(7)
	v_mfma_f32_16x16x32_bf16 v[60:63], v[152:155], v[184:187], v[60:63]
	v_mfma_f32_16x16x32_bf16 v[56:59], v[160:163], v[184:187], v[56:59]
	s_waitcnt lgkmcnt(5)
	v_mfma_f32_16x16x32_bf16 v[44:47], v[152:155], v[192:195], v[44:47]
	v_mfma_f32_16x16x32_bf16 v[40:43], v[160:163], v[192:195], v[40:43]
	s_waitcnt lgkmcnt(3)
	v_mfma_f32_16x16x32_bf16 v[28:31], v[152:155], v[200:203], v[28:31]
	v_mfma_f32_16x16x32_bf16 v[24:27], v[160:163], v[200:203], v[24:27]
	s_waitcnt lgkmcnt(1)
	v_mfma_f32_16x16x32_bf16 v[12:15], v[152:155], v[228:231], v[12:15]
	v_mfma_f32_16x16x32_bf16 v[8:11], v[160:163], v[228:231], v[8:11]
	v_mfma_f32_16x16x32_bf16 v[60:63], v[156:159], v[188:191], v[60:63]
	v_mfma_f32_16x16x32_bf16 v[56:59], v[164:167], v[188:191], v[56:59]
	v_mfma_f32_16x16x32_bf16 v[44:47], v[156:159], v[196:199], v[44:47]
	v_mfma_f32_16x16x32_bf16 v[40:43], v[164:167], v[196:199], v[40:43]
	v_mfma_f32_16x16x32_bf16 v[28:31], v[156:159], v[204:207], v[28:31]
	v_mfma_f32_16x16x32_bf16 v[24:27], v[164:167], v[204:207], v[24:27]
	s_waitcnt lgkmcnt(0)
	v_mfma_f32_16x16x32_bf16 v[12:15], v[156:159], v[240:243], v[12:15]
	v_mfma_f32_16x16x32_bf16 v[8:11], v[164:167], v[240:243], v[8:11]
	s_setprio 0
	s_setprio 1
	v_mfma_f32_16x16x32_bf16 v[52:55], v[168:171], v[184:187], v[52:55]
	v_mfma_f32_16x16x32_bf16 v[48:51], v[176:179], v[184:187], v[48:51]
	v_mfma_f32_16x16x32_bf16 v[36:39], v[168:171], v[192:195], v[36:39]
	v_mfma_f32_16x16x32_bf16 v[32:35], v[176:179], v[192:195], v[32:35]
	v_mfma_f32_16x16x32_bf16 v[20:23], v[168:171], v[200:203], v[20:23]
	v_mfma_f32_16x16x32_bf16 v[16:19], v[176:179], v[200:203], v[16:19]
	v_mfma_f32_16x16x32_bf16 v[4:7], v[168:171], v[228:231], v[4:7]
	v_mfma_f32_16x16x32_bf16 v[0:3], v[176:179], v[228:231], v[0:3]
	v_mfma_f32_16x16x32_bf16 v[52:55], v[172:175], v[188:191], v[52:55]
	v_mfma_f32_16x16x32_bf16 v[48:51], v[180:183], v[188:191], v[48:51]
	v_mfma_f32_16x16x32_bf16 v[36:39], v[172:175], v[196:199], v[36:39]
	v_mfma_f32_16x16x32_bf16 v[32:35], v[180:183], v[196:199], v[32:35]
	v_mfma_f32_16x16x32_bf16 v[20:23], v[172:175], v[204:207], v[20:23]
	v_mfma_f32_16x16x32_bf16 v[16:19], v[180:183], v[204:207], v[16:19]
	v_mfma_f32_16x16x32_bf16 v[4:7], v[172:175], v[240:243], v[4:7]
	v_mfma_f32_16x16x32_bf16 v[0:3], v[180:183], v[240:243], v[0:3]
	s_setprio 0
	s_barrier
	s_add_i32 s38, s38, 2
	s_add_i32 s39, s39, 0x8000
	s_cmp_gt_u32 s38, 29
	s_cbranch_scc1 .LBB0_597
